# both GEMM K-loops: one s_nop 0 ahead of the closing waits of sub-phases 2 and 3 so all 128 MFMAs and the LDS read runs sit on 8-byte boundaries
# baseline (speedup 1.0000x reference)
.LBB0_133:
	s_or_b32 s36, s61, 1
	s_lshl_b64 s[30:31], s[36:37], 7
	s_add_u32 s51, s0, s30
	s_addc_u32 s4, s1, s31
	s_add_i32 s36, s61, 2
	s_lshl_b64 s[30:31], s[36:37], 7
	s_add_u32 s5, s0, s30
	s_addc_u32 s6, s1, s31
	s_and_b64 vcc, s[58:59], exec
	s_cselect_b32 vcc_hi, s40, s6
	s_cselect_b32 vcc_lo, s41, s5
	s_add_u32 s5, s42, s30
	s_addc_u32 s6, s43, s31
	s_and_b64 s[30:31], s[58:59], exec
	s_cselect_b32 s59, s10, s6
	s_cselect_b32 s58, s11, s5
	s_add_i32 s5, 0, 0x10000
	s_add_i32 s6, 0, 0x14000
	v_add_u32_e32 v140, s5, v251
	v_add_u32_e32 v156, s6, v251
	ds_read_b128 v[128:131], v140
	ds_read_b128 v[132:135], v140 offset:1024
	ds_read_b128 v[136:139], v140 offset:2048
	ds_read_b128 v[140:143], v140 offset:3072
	ds_read_b128 v[144:147], v156
	ds_read_b128 v[148:151], v156 offset:1024
	ds_read_b128 v[152:155], v156 offset:2048
	ds_read_b128 v[156:159], v156 offset:3072
	s_add_u32 s30, s51, 0x40000
	s_addc_u32 s31, s4, 0
	v_lshl_add_u64 v[192:193], s[30:31], 0, v[216:217]
	s_add_i32 m0, s20, 0xc000
	ds_read_b128 v[160:163], v233
	ds_read_b128 v[164:167], v233 offset:1024
	ds_read_b128 v[168:171], v233 offset:2048
	ds_read_b128 v[172:175], v233 offset:3072
	ds_read_b128 v[176:179], v233 offset:4096
	ds_read_b128 v[180:183], v233 offset:5120
	ds_read_b128 v[184:187], v233 offset:6144
	ds_read_b128 v[188:191], v233 offset:7168
	global_load_lds_dwordx4 v[192:193], off
	v_lshl_add_u64 v[192:193], s[30:31], 0, v[218:219]
	s_add_i32 m0, s20, 0xe000
	s_nop 0
	global_load_lds_dwordx4 v[192:193], off
	s_waitcnt vmcnt(8)
	s_waitcnt lgkmcnt(0)
	s_barrier
	s_setprio 1
	s_waitcnt lgkmcnt(0)
	v_mfma_f32_16x16x32_bf16 v[124:127], v[128:131], v[160:163], v[124:127]
	v_mfma_f32_16x16x32_bf16 v[120:123], v[136:139], v[160:163], v[120:123]
	v_mfma_f32_16x16x32_bf16 v[116:119], v[128:131], v[168:171], v[116:119]
	v_mfma_f32_16x16x32_bf16 v[112:115], v[136:139], v[168:171], v[112:115]
	v_mfma_f32_16x16x32_bf16 v[108:111], v[128:131], v[176:179], v[108:111]
	v_mfma_f32_16x16x32_bf16 v[104:107], v[136:139], v[176:179], v[104:107]
	v_mfma_f32_16x16x32_bf16 v[100:103], v[128:131], v[184:187], v[100:103]
	v_mfma_f32_16x16x32_bf16 v[96:99], v[136:139], v[184:187], v[96:99]
	v_mfma_f32_16x16x32_bf16 v[124:127], v[132:135], v[164:167], v[124:127]
	v_mfma_f32_16x16x32_bf16 v[120:123], v[140:143], v[164:167], v[120:123]
	v_mfma_f32_16x16x32_bf16 v[116:119], v[132:135], v[172:175], v[116:119]
	v_mfma_f32_16x16x32_bf16 v[112:115], v[140:143], v[172:175], v[112:115]
	v_mfma_f32_16x16x32_bf16 v[108:111], v[132:135], v[180:183], v[108:111]
	v_mfma_f32_16x16x32_bf16 v[104:107], v[140:143], v[180:183], v[104:107]
	v_mfma_f32_16x16x32_bf16 v[100:103], v[132:135], v[188:191], v[100:103]
	v_mfma_f32_16x16x32_bf16 v[96:99], v[140:143], v[188:191], v[96:99]
	s_setprio 0
	s_setprio 1
	v_mfma_f32_16x16x32_bf16 v[92:95], v[144:147], v[160:163], v[92:95]
	v_mfma_f32_16x16x32_bf16 v[88:91], v[152:155], v[160:163], v[88:91]
	v_mfma_f32_16x16x32_bf16 v[84:87], v[144:147], v[168:171], v[84:87]
	v_mfma_f32_16x16x32_bf16 v[80:83], v[152:155], v[168:171], v[80:83]
	v_mfma_f32_16x16x32_bf16 v[76:79], v[144:147], v[176:179], v[76:79]
	v_mfma_f32_16x16x32_bf16 v[72:75], v[152:155], v[176:179], v[72:75]
	v_mfma_f32_16x16x32_bf16 v[68:71], v[144:147], v[184:187], v[68:71]
	v_mfma_f32_16x16x32_bf16 v[64:67], v[152:155], v[184:187], v[64:67]
	v_mfma_f32_16x16x32_bf16 v[92:95], v[148:151], v[164:167], v[92:95]
	v_mfma_f32_16x16x32_bf16 v[88:91], v[156:159], v[164:167], v[88:91]
	v_mfma_f32_16x16x32_bf16 v[84:87], v[148:151], v[172:175], v[84:87]
	v_mfma_f32_16x16x32_bf16 v[80:83], v[156:159], v[172:175], v[80:83]
	v_mfma_f32_16x16x32_bf16 v[76:79], v[148:151], v[180:183], v[76:79]
	v_mfma_f32_16x16x32_bf16 v[72:75], v[156:159], v[180:183], v[72:75]
	v_mfma_f32_16x16x32_bf16 v[68:71], v[148:151], v[188:191], v[68:71]
	v_mfma_f32_16x16x32_bf16 v[64:67], v[156:159], v[188:191], v[64:67]
	s_setprio 0
	s_barrier
	s_add_i32 s4, s5, s17
	v_lshl_add_u64 v[192:193], s[58:59], 0, v[216:217]
	s_mov_b32 m0, s4
	ds_read_b128 v[160:163], v233 offset:16384
	ds_read_b128 v[164:167], v233 offset:17408
	ds_read_b128 v[168:171], v233 offset:18432
	ds_read_b128 v[172:175], v233 offset:19456
	ds_read_b128 v[176:179], v233 offset:20480
	ds_read_b128 v[180:183], v233 offset:21504
	ds_read_b128 v[184:187], v233 offset:22528
	ds_read_b128 v[188:191], v233 offset:23552
	global_load_lds_dwordx4 v[192:193], off
	s_add_i32 m0, s4, 0x2000
	s_add_u32 s30, s58, 0x40000
	v_lshl_add_u64 v[194:195], s[58:59], 0, v[218:219]
	s_addc_u32 s31, s59, 0
	s_add_i32 s4, s6, s17
	global_load_lds_dwordx4 v[194:195], off
	v_lshl_add_u64 v[196:197], s[30:31], 0, v[216:217]
	s_mov_b32 m0, s4
	v_lshl_add_u64 v[198:199], vcc, 0, v[218:219]
	global_load_lds_dwordx4 v[196:197], off
	v_lshl_add_u64 v[196:197], s[30:31], 0, v[218:219]
	s_add_i32 m0, s4, 0x2000
	s_nop 0
	global_load_lds_dwordx4 v[196:197], off
	v_lshl_add_u64 v[196:197], vcc, 0, v[216:217]
	s_mov_b32 m0, s20
	s_nop 0
	global_load_lds_dwordx4 v[196:197], off
	s_mov_b32 m0, s21
	s_nop 0
	global_load_lds_dwordx4 v[198:199], off
	s_nop 0
	s_waitcnt vmcnt(8)
	s_waitcnt lgkmcnt(0)
	s_barrier
	s_setprio 1
	s_waitcnt lgkmcnt(0)
	v_mfma_f32_16x16x32_bf16 v[60:63], v[128:131], v[160:163], v[60:63]
	v_mfma_f32_16x16x32_bf16 v[56:59], v[136:139], v[160:163], v[56:59]
	v_mfma_f32_16x16x32_bf16 v[52:55], v[128:131], v[168:171], v[52:55]
	v_mfma_f32_16x16x32_bf16 v[48:51], v[136:139], v[168:171], v[48:51]
	v_mfma_f32_16x16x32_bf16 v[44:47], v[128:131], v[176:179], v[44:47]
	v_mfma_f32_16x16x32_bf16 v[40:43], v[136:139], v[176:179], v[40:43]
	v_mfma_f32_16x16x32_bf16 v[36:39], v[128:131], v[184:187], v[36:39]
	v_mfma_f32_16x16x32_bf16 v[32:35], v[136:139], v[184:187], v[32:35]
	v_mfma_f32_16x16x32_bf16 v[60:63], v[132:135], v[164:167], v[60:63]
	v_mfma_f32_16x16x32_bf16 v[56:59], v[140:143], v[164:167], v[56:59]
	v_mfma_f32_16x16x32_bf16 v[52:55], v[132:135], v[172:175], v[52:55]
	v_mfma_f32_16x16x32_bf16 v[48:51], v[140:143], v[172:175], v[48:51]
	v_mfma_f32_16x16x32_bf16 v[44:47], v[132:135], v[180:183], v[44:47]
	v_mfma_f32_16x16x32_bf16 v[40:43], v[140:143], v[180:183], v[40:43]
	v_mfma_f32_16x16x32_bf16 v[36:39], v[132:135], v[188:191], v[36:39]
	v_mfma_f32_16x16x32_bf16 v[32:35], v[140:143], v[188:191], v[32:35]
	s_setprio 0
	s_setprio 1
	v_mfma_f32_16x16x32_bf16 v[28:31], v[144:147], v[160:163], v[28:31]
	v_mfma_f32_16x16x32_bf16 v[24:27], v[152:155], v[160:163], v[24:27]
	v_mfma_f32_16x16x32_bf16 v[20:23], v[144:147], v[168:171], v[20:23]
	v_mfma_f32_16x16x32_bf16 v[16:19], v[152:155], v[168:171], v[16:19]
	v_mfma_f32_16x16x32_bf16 v[12:15], v[144:147], v[176:179], v[12:15]
	v_mfma_f32_16x16x32_bf16 v[8:11], v[152:155], v[176:179], v[8:11]
	v_mfma_f32_16x16x32_bf16 v[4:7], v[144:147], v[184:187], v[4:7]
	v_mfma_f32_16x16x32_bf16 v[0:3], v[152:155], v[184:187], v[0:3]
	v_mfma_f32_16x16x32_bf16 v[28:31], v[148:151], v[164:167], v[28:31]
	v_mfma_f32_16x16x32_bf16 v[24:27], v[156:159], v[164:167], v[24:27]
	v_mfma_f32_16x16x32_bf16 v[20:23], v[148:151], v[172:175], v[20:23]
	v_mfma_f32_16x16x32_bf16 v[16:19], v[156:159], v[172:175], v[16:19]
	v_mfma_f32_16x16x32_bf16 v[12:15], v[148:151], v[180:183], v[12:15]
	v_mfma_f32_16x16x32_bf16 v[8:11], v[156:159], v[180:183], v[8:11]
	v_mfma_f32_16x16x32_bf16 v[4:7], v[148:151], v[188:191], v[4:7]
	v_mfma_f32_16x16x32_bf16 v[0:3], v[156:159], v[188:191], v[0:3]
	s_setprio 0
	s_barrier
	s_add_i32 s4, 0, 0x18000
	s_add_i32 s5, 0, 0x1c000
	v_add_u32_e32 v140, s4, v251
	v_add_u32_e32 v156, s5, v251
	ds_read_b128 v[128:131], v140
	ds_read_b128 v[132:135], v140 offset:1024
	ds_read_b128 v[136:139], v140 offset:2048
	ds_read_b128 v[140:143], v140 offset:3072
	ds_read_b128 v[144:147], v156
	ds_read_b128 v[148:151], v156 offset:1024
	ds_read_b128 v[152:155], v156 offset:2048
	ds_read_b128 v[156:159], v156 offset:3072
	s_add_u32 s30, vcc_lo, 0x40000
	s_addc_u32 s31, vcc_hi, 0
	s_mov_b32 m0, s24
	v_lshl_add_u64 v[200:201], s[30:31], 0, v[216:217]
	ds_read_b128 v[160:163], v233 offset:32768
	ds_read_b128 v[164:167], v233 offset:33792
	ds_read_b128 v[168:171], v233 offset:34816
	ds_read_b128 v[172:175], v233 offset:35840
	ds_read_b128 v[176:179], v233 offset:36864
	ds_read_b128 v[180:183], v233 offset:37888
	ds_read_b128 v[184:187], v233 offset:38912
	ds_read_b128 v[188:191], v233 offset:39936
	global_load_lds_dwordx4 v[200:201], off
	v_lshl_add_u64 v[200:201], s[30:31], 0, v[218:219]
	s_mov_b32 m0, s25
	s_nop 0
	global_load_lds_dwordx4 v[200:201], off
	s_nop 0
	s_waitcnt vmcnt(8)
	s_waitcnt lgkmcnt(0)
	s_barrier
	s_setprio 1
	s_waitcnt lgkmcnt(0)
	v_mfma_f32_16x16x32_bf16 v[124:127], v[128:131], v[160:163], v[124:127]
	v_mfma_f32_16x16x32_bf16 v[120:123], v[136:139], v[160:163], v[120:123]
	v_mfma_f32_16x16x32_bf16 v[116:119], v[128:131], v[168:171], v[116:119]
	v_mfma_f32_16x16x32_bf16 v[112:115], v[136:139], v[168:171], v[112:115]
	v_mfma_f32_16x16x32_bf16 v[108:111], v[128:131], v[176:179], v[108:111]
	v_mfma_f32_16x16x32_bf16 v[104:107], v[136:139], v[176:179], v[104:107]
	v_mfma_f32_16x16x32_bf16 v[100:103], v[128:131], v[184:187], v[100:103]
	v_mfma_f32_16x16x32_bf16 v[96:99], v[136:139], v[184:187], v[96:99]
	v_mfma_f32_16x16x32_bf16 v[124:127], v[132:135], v[164:167], v[124:127]
	v_mfma_f32_16x16x32_bf16 v[120:123], v[140:143], v[164:167], v[120:123]
	v_mfma_f32_16x16x32_bf16 v[116:119], v[132:135], v[172:175], v[116:119]
	v_mfma_f32_16x16x32_bf16 v[112:115], v[140:143], v[172:175], v[112:115]
	v_mfma_f32_16x16x32_bf16 v[108:111], v[132:135], v[180:183], v[108:111]
	v_mfma_f32_16x16x32_bf16 v[104:107], v[140:143], v[180:183], v[104:107]
	v_mfma_f32_16x16x32_bf16 v[100:103], v[132:135], v[188:191], v[100:103]
	v_mfma_f32_16x16x32_bf16 v[96:99], v[140:143], v[188:191], v[96:99]
	s_setprio 0
	s_setprio 1
	v_mfma_f32_16x16x32_bf16 v[92:95], v[144:147], v[160:163], v[92:95]
	v_mfma_f32_16x16x32_bf16 v[88:91], v[152:155], v[160:163], v[88:91]
	v_mfma_f32_16x16x32_bf16 v[84:87], v[144:147], v[168:171], v[84:87]
	v_mfma_f32_16x16x32_bf16 v[80:83], v[152:155], v[168:171], v[80:83]
	v_mfma_f32_16x16x32_bf16 v[76:79], v[144:147], v[176:179], v[76:79]
	v_mfma_f32_16x16x32_bf16 v[72:75], v[152:155], v[176:179], v[72:75]
	v_mfma_f32_16x16x32_bf16 v[68:71], v[144:147], v[184:187], v[68:71]
	v_mfma_f32_16x16x32_bf16 v[64:67], v[152:155], v[184:187], v[64:67]
	v_mfma_f32_16x16x32_bf16 v[92:95], v[148:151], v[164:167], v[92:95]
	v_mfma_f32_16x16x32_bf16 v[88:91], v[156:159], v[164:167], v[88:91]
	v_mfma_f32_16x16x32_bf16 v[84:87], v[148:151], v[172:175], v[84:87]
	v_mfma_f32_16x16x32_bf16 v[80:83], v[156:159], v[172:175], v[80:83]
	v_mfma_f32_16x16x32_bf16 v[76:79], v[148:151], v[180:183], v[76:79]
	v_mfma_f32_16x16x32_bf16 v[72:75], v[156:159], v[180:183], v[72:75]
	v_mfma_f32_16x16x32_bf16 v[68:71], v[148:151], v[188:191], v[68:71]
	v_mfma_f32_16x16x32_bf16 v[64:67], v[156:159], v[188:191], v[64:67]
	s_setprio 0
	s_barrier
	s_add_i32 s4, s4, s17
	v_lshl_add_u64 v[192:193], v[192:193], 0, s[52:53]
	s_mov_b32 m0, s4
	ds_read_b128 v[160:163], v233 offset:49152
	ds_read_b128 v[164:167], v233 offset:50176
	ds_read_b128 v[168:171], v233 offset:51200
	ds_read_b128 v[172:175], v233 offset:52224
	ds_read_b128 v[176:179], v233 offset:53248
	ds_read_b128 v[180:183], v233 offset:54272
	ds_read_b128 v[184:187], v233 offset:55296
	ds_read_b128 v[188:191], v233 offset:56320
	global_load_lds_dwordx4 v[192:193], off
	s_add_i32 m0, s4, 0x2000
	s_add_u32 s30, s58, 0x40080
	v_lshl_add_u64 v[192:193], v[194:195], 0, s[52:53]
	s_addc_u32 s31, s59, 0
	s_add_i32 s4, s5, s17
	global_load_lds_dwordx4 v[192:193], off
	v_lshl_add_u64 v[192:193], s[30:31], 0, v[216:217]
	s_mov_b32 m0, s4
	s_nop 0
	global_load_lds_dwordx4 v[192:193], off
	v_lshl_add_u64 v[192:193], s[30:31], 0, v[218:219]
	s_add_i32 m0, s4, 0x2000
	s_nop 0
	global_load_lds_dwordx4 v[192:193], off
	v_lshl_add_u64 v[192:193], v[196:197], 0, s[52:53]
	s_mov_b32 m0, s15
	s_nop 0
	global_load_lds_dwordx4 v[192:193], off
	v_lshl_add_u64 v[192:193], v[198:199], 0, s[52:53]
	s_mov_b32 m0, s33
	s_nop 0
	global_load_lds_dwordx4 v[192:193], off
	s_waitcnt vmcnt(8)
	s_waitcnt lgkmcnt(0)
	s_barrier
	s_setprio 1
	s_waitcnt lgkmcnt(0)
	v_mfma_f32_16x16x32_bf16 v[60:63], v[128:131], v[160:163], v[60:63]
	v_mfma_f32_16x16x32_bf16 v[56:59], v[136:139], v[160:163], v[56:59]
	v_mfma_f32_16x16x32_bf16 v[52:55], v[128:131], v[168:171], v[52:55]
	v_mfma_f32_16x16x32_bf16 v[48:51], v[136:139], v[168:171], v[48:51]
	v_mfma_f32_16x16x32_bf16 v[44:47], v[128:131], v[176:179], v[44:47]
	v_mfma_f32_16x16x32_bf16 v[40:43], v[136:139], v[176:179], v[40:43]
	v_mfma_f32_16x16x32_bf16 v[36:39], v[128:131], v[184:187], v[36:39]
	v_mfma_f32_16x16x32_bf16 v[32:35], v[136:139], v[184:187], v[32:35]
	v_mfma_f32_16x16x32_bf16 v[60:63], v[132:135], v[164:167], v[60:63]
	v_mfma_f32_16x16x32_bf16 v[56:59], v[140:143], v[164:167], v[56:59]
	v_mfma_f32_16x16x32_bf16 v[52:55], v[132:135], v[172:175], v[52:55]
	v_mfma_f32_16x16x32_bf16 v[48:51], v[140:143], v[172:175], v[48:51]
	v_mfma_f32_16x16x32_bf16 v[44:47], v[132:135], v[180:183], v[44:47]
	v_mfma_f32_16x16x32_bf16 v[40:43], v[140:143], v[180:183], v[40:43]
	v_mfma_f32_16x16x32_bf16 v[36:39], v[132:135], v[188:191], v[36:39]
	v_mfma_f32_16x16x32_bf16 v[32:35], v[140:143], v[188:191], v[32:35]
	s_setprio 0
	s_setprio 1
	v_mfma_f32_16x16x32_bf16 v[28:31], v[144:147], v[160:163], v[28:31]
	v_mfma_f32_16x16x32_bf16 v[24:27], v[152:155], v[160:163], v[24:27]
	v_mfma_f32_16x16x32_bf16 v[20:23], v[144:147], v[168:171], v[20:23]
	v_mfma_f32_16x16x32_bf16 v[16:19], v[152:155], v[168:171], v[16:19]
	v_mfma_f32_16x16x32_bf16 v[12:15], v[144:147], v[176:179], v[12:15]
	v_mfma_f32_16x16x32_bf16 v[8:11], v[152:155], v[176:179], v[8:11]
	v_mfma_f32_16x16x32_bf16 v[4:7], v[144:147], v[184:187], v[4:7]
	v_mfma_f32_16x16x32_bf16 v[0:3], v[152:155], v[184:187], v[0:3]
	v_mfma_f32_16x16x32_bf16 v[28:31], v[148:151], v[164:167], v[28:31]
	v_mfma_f32_16x16x32_bf16 v[24:27], v[156:159], v[164:167], v[24:27]
	v_mfma_f32_16x16x32_bf16 v[20:23], v[148:151], v[172:175], v[20:23]
	v_mfma_f32_16x16x32_bf16 v[16:19], v[156:159], v[172:175], v[16:19]
	v_mfma_f32_16x16x32_bf16 v[12:15], v[148:151], v[180:183], v[12:15]
	v_mfma_f32_16x16x32_bf16 v[8:11], v[156:159], v[180:183], v[8:11]
	v_mfma_f32_16x16x32_bf16 v[4:7], v[148:151], v[188:191], v[4:7]
	v_mfma_f32_16x16x32_bf16 v[0:3], v[156:159], v[188:191], v[0:3]
	s_setprio 0
	s_barrier
	s_cmp_ge_i32 s36, s47
	s_mov_b32 s61, s36
	s_cbranch_scc1 .LBB0_147

.LBB0_453:
	s_add_u32 s31, s18, 0xfffc0080
	s_addc_u32 s46, s19, -1
	s_add_i32 s51, 0, 0x10000
	s_cmp_eq_u32 s30, 12
	s_cselect_b32 s49, s11, s46
	s_cselect_b32 s48, s10, s31
	s_cselect_b32 s47, s59, s16
	s_cselect_b32 s46, s58, s1
	s_add_i32 s31, 0, 0x14000
	v_add_u32_e32 v154, s51, v158
	v_add_u32_e32 v165, s31, v158
	ds_read_b128 v[128:131], v154
	ds_read_b128 v[132:135], v154 offset:1024
	ds_read_b128 v[150:153], v154 offset:2048
	ds_read_b128 v[154:157], v154 offset:3072
	ds_read_b128 v[166:169], v165
	ds_read_b128 v[170:173], v165 offset:1024
	ds_read_b128 v[174:177], v165 offset:2048
	ds_read_b128 v[178:181], v165 offset:3072
	v_lshl_add_u64 v[206:207], s[18:19], 0, v[146:147]
	s_add_i32 m0, s41, 0xc000
	ds_read_b128 v[182:185], v164
	ds_read_b128 v[186:189], v164 offset:1024
	ds_read_b128 v[190:193], v164 offset:2048
	ds_read_b128 v[194:197], v164 offset:3072
	ds_read_b128 v[198:201], v164 offset:4096
	ds_read_b128 v[202:205], v164 offset:5120
	ds_read_b128 v[216:219], v164 offset:6144
	ds_read_b128 v[224:227], v164 offset:7168
	global_load_lds_dwordx4 v[206:207], off
	v_lshl_add_u64 v[206:207], s[18:19], 0, v[148:149]
	s_add_i32 m0, s41, 0xe000
	s_nop 0
	global_load_lds_dwordx4 v[206:207], off
	s_waitcnt vmcnt(8)
	s_waitcnt lgkmcnt(0)
	s_barrier
	s_setprio 1
	s_waitcnt lgkmcnt(0)
	v_mfma_f32_16x16x32_bf16 v[124:127], v[128:131], v[182:185], v[124:127]
	v_mfma_f32_16x16x32_bf16 v[120:123], v[150:153], v[182:185], v[120:123]
	v_mfma_f32_16x16x32_bf16 v[108:111], v[128:131], v[190:193], v[108:111]
	v_mfma_f32_16x16x32_bf16 v[104:107], v[150:153], v[190:193], v[104:107]
	v_mfma_f32_16x16x32_bf16 v[92:95], v[128:131], v[198:201], v[92:95]
	v_mfma_f32_16x16x32_bf16 v[88:91], v[150:153], v[198:201], v[88:91]
	v_mfma_f32_16x16x32_bf16 v[76:79], v[128:131], v[216:219], v[76:79]
	v_mfma_f32_16x16x32_bf16 v[72:75], v[150:153], v[216:219], v[72:75]
	v_mfma_f32_16x16x32_bf16 v[124:127], v[132:135], v[186:189], v[124:127]
	v_mfma_f32_16x16x32_bf16 v[120:123], v[154:157], v[186:189], v[120:123]
	v_mfma_f32_16x16x32_bf16 v[108:111], v[132:135], v[194:197], v[108:111]
	v_mfma_f32_16x16x32_bf16 v[104:107], v[154:157], v[194:197], v[104:107]
	v_mfma_f32_16x16x32_bf16 v[92:95], v[132:135], v[202:205], v[92:95]
	v_mfma_f32_16x16x32_bf16 v[88:91], v[154:157], v[202:205], v[88:91]
	v_mfma_f32_16x16x32_bf16 v[76:79], v[132:135], v[224:227], v[76:79]
	v_mfma_f32_16x16x32_bf16 v[72:75], v[154:157], v[224:227], v[72:75]
	s_setprio 0
	s_setprio 1
	v_mfma_f32_16x16x32_bf16 v[116:119], v[166:169], v[182:185], v[116:119]
	v_mfma_f32_16x16x32_bf16 v[112:115], v[174:177], v[182:185], v[112:115]
	v_mfma_f32_16x16x32_bf16 v[100:103], v[166:169], v[190:193], v[100:103]
	v_mfma_f32_16x16x32_bf16 v[96:99], v[174:177], v[190:193], v[96:99]
	v_mfma_f32_16x16x32_bf16 v[84:87], v[166:169], v[198:201], v[84:87]
	v_mfma_f32_16x16x32_bf16 v[80:83], v[174:177], v[198:201], v[80:83]
	v_mfma_f32_16x16x32_bf16 v[68:71], v[166:169], v[216:219], v[68:71]
	v_mfma_f32_16x16x32_bf16 v[64:67], v[174:177], v[216:219], v[64:67]
	v_mfma_f32_16x16x32_bf16 v[116:119], v[170:173], v[186:189], v[116:119]
	v_mfma_f32_16x16x32_bf16 v[112:115], v[178:181], v[186:189], v[112:115]
	v_mfma_f32_16x16x32_bf16 v[100:103], v[170:173], v[194:197], v[100:103]
	v_mfma_f32_16x16x32_bf16 v[96:99], v[178:181], v[194:197], v[96:99]
	v_mfma_f32_16x16x32_bf16 v[84:87], v[170:173], v[202:205], v[84:87]
	v_mfma_f32_16x16x32_bf16 v[80:83], v[178:181], v[202:205], v[80:83]
	v_mfma_f32_16x16x32_bf16 v[68:71], v[170:173], v[224:227], v[68:71]
	v_mfma_f32_16x16x32_bf16 v[64:67], v[178:181], v[224:227], v[64:67]
	s_setprio 0
	s_barrier
	s_add_i32 s51, s51, s40
	v_lshl_add_u64 v[206:207], s[46:47], 0, v[136:137]
	s_mov_b32 m0, s51
	ds_read_b128 v[182:185], v164 offset:16384
	ds_read_b128 v[186:189], v164 offset:17408
	ds_read_b128 v[190:193], v164 offset:18432
	ds_read_b128 v[194:197], v164 offset:19456
	ds_read_b128 v[198:201], v164 offset:20480
	ds_read_b128 v[202:205], v164 offset:21504
	ds_read_b128 v[216:219], v164 offset:22528
	ds_read_b128 v[224:227], v164 offset:23552
	global_load_lds_dwordx4 v[206:207], off
	s_add_i32 m0, s51, 0x2000
	s_add_u32 s62, s46, 0x40000
	v_lshl_add_u64 v[250:251], s[46:47], 0, v[138:139]
	s_addc_u32 s63, s47, 0
	s_add_i32 s31, s31, s40
	global_load_lds_dwordx4 v[250:251], off
	v_lshl_add_u64 v[238:239], s[62:63], 0, v[136:137]
	s_mov_b32 m0, s31
	v_lshl_add_u64 v[244:245], s[48:49], 0, v[138:139]
	global_load_lds_dwordx4 v[238:239], off
	v_lshl_add_u64 v[238:239], s[62:63], 0, v[138:139]
	s_add_i32 m0, s31, 0x2000
	s_nop 0
	global_load_lds_dwordx4 v[238:239], off
	v_lshl_add_u64 v[238:239], s[48:49], 0, v[136:137]
	s_mov_b32 m0, s41
	s_nop 0
	global_load_lds_dwordx4 v[238:239], off
	s_mov_b32 m0, s33
	s_nop 0
	global_load_lds_dwordx4 v[244:245], off
	s_nop 0
	s_waitcnt vmcnt(8)
	s_waitcnt lgkmcnt(0)
	s_barrier
	s_setprio 1
	s_waitcnt lgkmcnt(0)
	v_mfma_f32_16x16x32_bf16 v[60:63], v[128:131], v[182:185], v[60:63]
	v_mfma_f32_16x16x32_bf16 v[56:59], v[150:153], v[182:185], v[56:59]
	v_mfma_f32_16x16x32_bf16 v[44:47], v[128:131], v[190:193], v[44:47]
	v_mfma_f32_16x16x32_bf16 v[40:43], v[150:153], v[190:193], v[40:43]
	v_mfma_f32_16x16x32_bf16 v[28:31], v[128:131], v[198:201], v[28:31]
	v_mfma_f32_16x16x32_bf16 v[24:27], v[150:153], v[198:201], v[24:27]
	v_mfma_f32_16x16x32_bf16 v[12:15], v[128:131], v[216:219], v[12:15]
	v_mfma_f32_16x16x32_bf16 v[8:11], v[150:153], v[216:219], v[8:11]
	v_mfma_f32_16x16x32_bf16 v[60:63], v[132:135], v[186:189], v[60:63]
	v_mfma_f32_16x16x32_bf16 v[56:59], v[154:157], v[186:189], v[56:59]
	v_mfma_f32_16x16x32_bf16 v[44:47], v[132:135], v[194:197], v[44:47]
	v_mfma_f32_16x16x32_bf16 v[40:43], v[154:157], v[194:197], v[40:43]
	v_mfma_f32_16x16x32_bf16 v[28:31], v[132:135], v[202:205], v[28:31]
	v_mfma_f32_16x16x32_bf16 v[24:27], v[154:157], v[202:205], v[24:27]
	v_mfma_f32_16x16x32_bf16 v[12:15], v[132:135], v[224:227], v[12:15]
	v_mfma_f32_16x16x32_bf16 v[8:11], v[154:157], v[224:227], v[8:11]
	s_setprio 0
	s_setprio 1
	v_mfma_f32_16x16x32_bf16 v[52:55], v[166:169], v[182:185], v[52:55]
	v_mfma_f32_16x16x32_bf16 v[48:51], v[174:177], v[182:185], v[48:51]
	v_mfma_f32_16x16x32_bf16 v[36:39], v[166:169], v[190:193], v[36:39]
	v_mfma_f32_16x16x32_bf16 v[32:35], v[174:177], v[190:193], v[32:35]
	v_mfma_f32_16x16x32_bf16 v[20:23], v[166:169], v[198:201], v[20:23]
	v_mfma_f32_16x16x32_bf16 v[16:19], v[174:177], v[198:201], v[16:19]
	v_mfma_f32_16x16x32_bf16 v[4:7], v[166:169], v[216:219], v[4:7]
	v_mfma_f32_16x16x32_bf16 v[0:3], v[174:177], v[216:219], v[0:3]
	v_mfma_f32_16x16x32_bf16 v[52:55], v[170:173], v[186:189], v[52:55]
	v_mfma_f32_16x16x32_bf16 v[48:51], v[178:181], v[186:189], v[48:51]
	v_mfma_f32_16x16x32_bf16 v[36:39], v[170:173], v[194:197], v[36:39]
	v_mfma_f32_16x16x32_bf16 v[32:35], v[178:181], v[194:197], v[32:35]
	v_mfma_f32_16x16x32_bf16 v[20:23], v[170:173], v[202:205], v[20:23]
	v_mfma_f32_16x16x32_bf16 v[16:19], v[178:181], v[202:205], v[16:19]
	v_mfma_f32_16x16x32_bf16 v[4:7], v[170:173], v[224:227], v[4:7]
	v_mfma_f32_16x16x32_bf16 v[0:3], v[178:181], v[224:227], v[0:3]
	s_setprio 0
	s_barrier
	s_add_i32 s31, 0, 0x18000
	s_add_i32 s51, 0, 0x1c000
	v_add_u32_e32 v154, s31, v158
	v_add_u32_e32 v165, s51, v158
	ds_read_b128 v[128:131], v154
	ds_read_b128 v[132:135], v154 offset:1024
	ds_read_b128 v[150:153], v154 offset:2048
	ds_read_b128 v[154:157], v154 offset:3072
	ds_read_b128 v[166:169], v165
	ds_read_b128 v[170:173], v165 offset:1024
	ds_read_b128 v[174:177], v165 offset:2048
	ds_read_b128 v[178:181], v165 offset:3072
	s_add_u32 s48, s48, 0x40000
	s_addc_u32 s49, s49, 0
	s_mov_b32 m0, s15
	v_lshl_add_u64 v[246:247], s[48:49], 0, v[136:137]
	ds_read_b128 v[182:185], v164 offset:32768
	ds_read_b128 v[186:189], v164 offset:33792
	ds_read_b128 v[190:193], v164 offset:34816
	ds_read_b128 v[194:197], v164 offset:35840
	ds_read_b128 v[198:201], v164 offset:36864
	ds_read_b128 v[202:205], v164 offset:37888
	ds_read_b128 v[216:219], v164 offset:38912
	ds_read_b128 v[224:227], v164 offset:39936
	global_load_lds_dwordx4 v[246:247], off
	v_lshl_add_u64 v[246:247], s[48:49], 0, v[138:139]
	s_mov_b32 m0, s21
	s_nop 0
	global_load_lds_dwordx4 v[246:247], off
	s_nop 0
	s_waitcnt vmcnt(8)
	s_waitcnt lgkmcnt(0)
	s_barrier
	s_setprio 1
	s_waitcnt lgkmcnt(0)
	v_mfma_f32_16x16x32_bf16 v[124:127], v[128:131], v[182:185], v[124:127]
	v_mfma_f32_16x16x32_bf16 v[120:123], v[150:153], v[182:185], v[120:123]
	v_mfma_f32_16x16x32_bf16 v[108:111], v[128:131], v[190:193], v[108:111]
	v_mfma_f32_16x16x32_bf16 v[104:107], v[150:153], v[190:193], v[104:107]
	v_mfma_f32_16x16x32_bf16 v[92:95], v[128:131], v[198:201], v[92:95]
	v_mfma_f32_16x16x32_bf16 v[88:91], v[150:153], v[198:201], v[88:91]
	v_mfma_f32_16x16x32_bf16 v[76:79], v[128:131], v[216:219], v[76:79]
	v_mfma_f32_16x16x32_bf16 v[72:75], v[150:153], v[216:219], v[72:75]
	v_mfma_f32_16x16x32_bf16 v[124:127], v[132:135], v[186:189], v[124:127]
	v_mfma_f32_16x16x32_bf16 v[120:123], v[154:157], v[186:189], v[120:123]
	v_mfma_f32_16x16x32_bf16 v[108:111], v[132:135], v[194:197], v[108:111]
	v_mfma_f32_16x16x32_bf16 v[104:107], v[154:157], v[194:197], v[104:107]
	v_mfma_f32_16x16x32_bf16 v[92:95], v[132:135], v[202:205], v[92:95]
	v_mfma_f32_16x16x32_bf16 v[88:91], v[154:157], v[202:205], v[88:91]
	v_mfma_f32_16x16x32_bf16 v[76:79], v[132:135], v[224:227], v[76:79]
	v_mfma_f32_16x16x32_bf16 v[72:75], v[154:157], v[224:227], v[72:75]
	s_setprio 0
	s_setprio 1
	v_mfma_f32_16x16x32_bf16 v[116:119], v[166:169], v[182:185], v[116:119]
	v_mfma_f32_16x16x32_bf16 v[112:115], v[174:177], v[182:185], v[112:115]
	v_mfma_f32_16x16x32_bf16 v[100:103], v[166:169], v[190:193], v[100:103]
	v_mfma_f32_16x16x32_bf16 v[96:99], v[174:177], v[190:193], v[96:99]
	v_mfma_f32_16x16x32_bf16 v[84:87], v[166:169], v[198:201], v[84:87]
	v_mfma_f32_16x16x32_bf16 v[80:83], v[174:177], v[198:201], v[80:83]
	v_mfma_f32_16x16x32_bf16 v[68:71], v[166:169], v[216:219], v[68:71]
	v_mfma_f32_16x16x32_bf16 v[64:67], v[174:177], v[216:219], v[64:67]
	v_mfma_f32_16x16x32_bf16 v[116:119], v[170:173], v[186:189], v[116:119]
	v_mfma_f32_16x16x32_bf16 v[112:115], v[178:181], v[186:189], v[112:115]
	v_mfma_f32_16x16x32_bf16 v[100:103], v[170:173], v[194:197], v[100:103]
	v_mfma_f32_16x16x32_bf16 v[96:99], v[178:181], v[194:197], v[96:99]
	v_mfma_f32_16x16x32_bf16 v[84:87], v[170:173], v[202:205], v[84:87]
	v_mfma_f32_16x16x32_bf16 v[80:83], v[178:181], v[202:205], v[80:83]
	v_mfma_f32_16x16x32_bf16 v[68:71], v[170:173], v[224:227], v[68:71]
	v_mfma_f32_16x16x32_bf16 v[64:67], v[178:181], v[224:227], v[64:67]
	s_setprio 0
	s_barrier
	s_add_i32 s31, s31, s40
	v_lshl_add_u64 v[206:207], v[206:207], 0, s[52:53]
	s_mov_b32 m0, s31
	ds_read_b128 v[182:185], v164 offset:49152
	ds_read_b128 v[186:189], v164 offset:50176
	ds_read_b128 v[190:193], v164 offset:51200
	ds_read_b128 v[194:197], v164 offset:52224
	ds_read_b128 v[198:201], v164 offset:53248
	ds_read_b128 v[202:205], v164 offset:54272
	ds_read_b128 v[216:219], v164 offset:55296
	ds_read_b128 v[224:227], v164 offset:56320
	global_load_lds_dwordx4 v[206:207], off
	s_add_i32 m0, s31, 0x2000
	s_add_u32 s46, s46, 0x40080
	v_lshl_add_u64 v[206:207], v[250:251], 0, s[52:53]
	s_addc_u32 s47, s47, 0
	s_add_i32 s31, s51, s40
	global_load_lds_dwordx4 v[206:207], off
	v_lshl_add_u64 v[206:207], s[46:47], 0, v[136:137]
	s_mov_b32 m0, s31
	s_nop 0
	global_load_lds_dwordx4 v[206:207], off
	v_lshl_add_u64 v[206:207], s[46:47], 0, v[138:139]
	s_add_i32 m0, s31, 0x2000
	s_nop 0
	global_load_lds_dwordx4 v[206:207], off
	v_lshl_add_u64 v[206:207], v[238:239], 0, s[52:53]
	s_mov_b32 m0, s24
	s_nop 0
	global_load_lds_dwordx4 v[206:207], off
	v_lshl_add_u64 v[206:207], v[244:245], 0, s[52:53]
	s_mov_b32 m0, s25
	s_nop 0
	global_load_lds_dwordx4 v[206:207], off
	s_waitcnt vmcnt(8)
	s_waitcnt lgkmcnt(0)
	s_barrier
	s_setprio 1
	s_waitcnt lgkmcnt(0)
	v_mfma_f32_16x16x32_bf16 v[60:63], v[128:131], v[182:185], v[60:63]
	v_mfma_f32_16x16x32_bf16 v[56:59], v[150:153], v[182:185], v[56:59]
	v_mfma_f32_16x16x32_bf16 v[44:47], v[128:131], v[190:193], v[44:47]
	v_mfma_f32_16x16x32_bf16 v[40:43], v[150:153], v[190:193], v[40:43]
	v_mfma_f32_16x16x32_bf16 v[28:31], v[128:131], v[198:201], v[28:31]
	v_mfma_f32_16x16x32_bf16 v[24:27], v[150:153], v[198:201], v[24:27]
	v_mfma_f32_16x16x32_bf16 v[12:15], v[128:131], v[216:219], v[12:15]
	v_mfma_f32_16x16x32_bf16 v[8:11], v[150:153], v[216:219], v[8:11]
	v_mfma_f32_16x16x32_bf16 v[60:63], v[132:135], v[186:189], v[60:63]
	v_mfma_f32_16x16x32_bf16 v[56:59], v[154:157], v[186:189], v[56:59]
	v_mfma_f32_16x16x32_bf16 v[44:47], v[132:135], v[194:197], v[44:47]
	v_mfma_f32_16x16x32_bf16 v[40:43], v[154:157], v[194:197], v[40:43]
	v_mfma_f32_16x16x32_bf16 v[28:31], v[132:135], v[202:205], v[28:31]
	v_mfma_f32_16x16x32_bf16 v[24:27], v[154:157], v[202:205], v[24:27]
	v_mfma_f32_16x16x32_bf16 v[12:15], v[132:135], v[224:227], v[12:15]
	v_mfma_f32_16x16x32_bf16 v[8:11], v[154:157], v[224:227], v[8:11]
	s_setprio 0
	s_setprio 1
	v_mfma_f32_16x16x32_bf16 v[52:55], v[166:169], v[182:185], v[52:55]
	v_mfma_f32_16x16x32_bf16 v[48:51], v[174:177], v[182:185], v[48:51]
	v_mfma_f32_16x16x32_bf16 v[36:39], v[166:169], v[190:193], v[36:39]
	v_mfma_f32_16x16x32_bf16 v[32:35], v[174:177], v[190:193], v[32:35]
	v_mfma_f32_16x16x32_bf16 v[20:23], v[166:169], v[198:201], v[20:23]
	v_mfma_f32_16x16x32_bf16 v[16:19], v[174:177], v[198:201], v[16:19]
	v_mfma_f32_16x16x32_bf16 v[4:7], v[166:169], v[216:219], v[4:7]
	v_mfma_f32_16x16x32_bf16 v[0:3], v[174:177], v[216:219], v[0:3]
	v_mfma_f32_16x16x32_bf16 v[52:55], v[170:173], v[186:189], v[52:55]
	v_mfma_f32_16x16x32_bf16 v[48:51], v[178:181], v[186:189], v[48:51]
	v_mfma_f32_16x16x32_bf16 v[36:39], v[170:173], v[194:197], v[36:39]
	v_mfma_f32_16x16x32_bf16 v[32:35], v[178:181], v[194:197], v[32:35]
	v_mfma_f32_16x16x32_bf16 v[20:23], v[170:173], v[202:205], v[20:23]
	v_mfma_f32_16x16x32_bf16 v[16:19], v[178:181], v[202:205], v[16:19]
	v_mfma_f32_16x16x32_bf16 v[4:7], v[170:173], v[224:227], v[4:7]
	v_mfma_f32_16x16x32_bf16 v[0:3], v[178:181], v[224:227], v[0:3]
	s_setprio 0
	s_barrier
	s_add_i32 s30, s30, 2
	s_add_u32 s18, s18, 0x100
	s_addc_u32 s19, s19, 0
	s_add_u32 s1, s1, 0x100
	s_addc_u32 s16, s16, 0
	s_cmp_gt_u32 s30, 13
	s_cbranch_scc0 .LBB0_453
	s_and_b64 vcc, exec, s[64:65]
	s_cbranch_vccz .LBB0_456
	s_barrier
